# prompt attention sweep: hand-written mask-free key-block body (183 VALU vs ~280) for the non-diagonal blocks; the diagonal block keeps the original masked body
# speedup vs baseline: 1.0029x; 1.0029x over previous
; template <bool sample> __device__ __forceinline__ void attn_task(const Args& a, LAS unsigned char* vl, int lane, int task) {
;     ...
; #pragma unroll
;         for (int s = 0; s < 8; ++s) x = __builtin_amdgcn_mfma_f32_32x32x16_bf16(kf[s], qf[s], x, 0, 0, 0);
;         u32x4 vr[8];
;         if (!cache) {
;             const bf16_t* vp = Pv + (size_t)((sample ? row0 : row0 + kp0) + 2 * (lane >> 2)) * DM + hd * HD + (lane & 3) * 8;
; #pragma unroll
;             for (int i = 0; i < 8; ++i) vr[i] = *(const u32x4*)(vp + (i >> 2) * DM + (i & 3) * 32);
;         } else {
;             const float* vpc = a.cv + (((size_t)seq * PAST + kp0 + 2 * (lane >> 2)) * NHEAD + hd) * HD + (lane & 3) * 8;
; #pragma unroll
;             for (int i = 0; i < 8; ++i) { const float* vp = vpc + (i >> 2) * DM + (i & 3) * 32;
;                 const f32x4 x0 = *(const f32x4*)vp, x1 = *(const f32x4*)(vp + 4);
;                 vr[i].x = pk2(x0[0], x0[1]); vr[i].y = pk2(x0[2], x0[3]); vr[i].z = pk2(x1[0], x1[1]); vr[i].w = pk2(x1[2], x1[3]);
;                 if (i == 3) asm volatile("" ::: "memory"); }
;         }
;         if (!sample) {
;             const bf16_t* kp = KSW + ksw_off(seq * NGRP_ + (kb > 0 ? kb - 1 : 0), hd) + lane * 8;
; #pragma unroll
;             for (int s = 0; s < 8; ++s) kf[s] = *(const bf16x8*)(kp + 512 * s);
;         }
;         __builtin_amdgcn_sched_barrier(0);
;         float l1[16];
; #pragma unroll
;         for (int i = 0; i < 16; ++i) {
;             const float z = x[i];
;             const float e = __builtin_amdgcn_exp2f(-__builtin_fabsf(z));
;             const float sp = fmaxf(z, 0.f) + __builtin_amdgcn_logf(1.f + e);
;             const int key = kp0 + 8 * (i >> 2) + 4 * h + (i & 3);
;             l1[i] = key < qpos ? -sp : 0.f;
;         }
;         float gs[4], og[4], A[4], tot = 0.f;
; #pragma unroll
;         for (int j = 0; j < 4; ++j) { gs[j] = (l1[4 * j] + l1[4 * j + 1]) + (l1[4 * j + 2] + l1[4 * j + 3]); og[j] = __shfl_xor(gs[j], 32); }
; #pragma unroll
;         for (int j = 3; j >= 0; --j) { A[j] = tot + (h == 0 ? og[j] : 0.f); tot += gs[j] + og[j]; }
;         float p[16];
; #pragma unroll
;         for (int j = 0; j < 4; ++j) {
;             float sfx = run + A[j];
; #pragma unroll
;             for (int i = 3; i >= 0; --i) {
;                 const int key = kp0 + 8 * j + 4 * h + i;
.Lsb_nm:
	s_waitcnt vmcnt(0)
	v_mfma_f32_32x32x16_bf16 v[64:79], v[136:139], v[80:83], 0
	s_min_u32 s0, s26, 1
	s_sub_i32 s0, s25, s0
	s_ashr_i32 s1, s0, 31
	s_lshl_b64 s[0:1], s[0:1], 16
	v_mfma_f32_32x32x16_bf16 v[64:79], v[132:135], v[84:87], v[64:79]
	v_mfma_f32_32x32x16_bf16 v[64:79], v[128:131], v[88:91], v[64:79]
	v_add_u32_e32 v128, s24, v219
	v_ashrrev_i32_e32 v129, 31, v128
	v_lshlrev_b64 v[128:129], 11, v[128:129]
	v_mfma_f32_32x32x16_bf16 v[64:79], v[124:127], v[92:95], v[64:79]
	v_lshl_add_u64 v[124:125], v[194:195], 0, v[128:129]
	global_load_dwordx4 v[144:147], v[124:125], off
	global_load_dwordx4 v[148:151], v[124:125], off offset:64
	global_load_dwordx4 v[152:155], v[124:125], off offset:128
	global_load_dwordx4 v[156:159], v[124:125], off offset:192
	global_load_dwordx4 v[160:163], v[124:125], off offset:2048
	global_load_dwordx4 v[164:167], v[124:125], off offset:2112
	global_load_dwordx4 v[168:171], v[124:125], off offset:2176
	global_load_dwordx4 v[172:175], v[124:125], off offset:2240
	v_mfma_f32_32x32x16_bf16 v[64:79], v[120:123], v[96:99], v[64:79]
	v_lshl_add_u64 v[120:121], v[196:197], 0, s[0:1]
	v_add_co_u32_e32 v140, vcc, s90, v120
	s_nop 1
	v_addc_co_u32_e32 v141, vcc, 0, v121, vcc
	v_mfma_f32_32x32x16_bf16 v[64:79], v[116:119], v[100:103], v[64:79]
	global_load_dwordx4 v[136:139], v[120:121], off
	global_load_dwordx4 v[132:135], v[120:121], off offset:1024
	global_load_dwordx4 v[128:131], v[120:121], off offset:2048
	global_load_dwordx4 v[124:127], v[120:121], off offset:3072
	s_nop 0
	global_load_dwordx4 v[120:123], v[140:141], off
	global_load_dwordx4 v[116:119], v[140:141], off offset:1024
	v_mfma_f32_32x32x16_bf16 v[64:79], v[112:115], v[104:107], v[64:79]
	global_load_dwordx4 v[112:115], v[140:141], off offset:2048
	s_nop 0
	global_load_dwordx4 v[140:143], v[140:141], off offset:3072
	v_mfma_f32_32x32x16_bf16 v[64:79], v[176:179], v[108:111], v[64:79]
	s_nop 11
	v_exp_f32_e64 v220, -|v64|
	v_exp_f32_e64 v221, -|v65|
	v_exp_f32_e64 v222, -|v66|
	v_exp_f32_e64 v223, -|v67|
	v_min_f32_e64 v224, 0, -v64
	v_min_f32_e64 v225, 0, -v65
	v_min_f32_e64 v226, 0, -v66
	v_min_f32_e64 v227, 0, -v67
	v_add_f32_e32 v220, 1.0, v220
	v_add_f32_e32 v221, 1.0, v221
	v_add_f32_e32 v222, 1.0, v222
	v_add_f32_e32 v223, 1.0, v223
	v_log_f32_e32 v220, v220
	v_log_f32_e32 v221, v221
	v_log_f32_e32 v222, v222
	v_log_f32_e32 v223, v223
	v_sub_f32_e32 v176, v224, v220
	v_sub_f32_e32 v177, v225, v221
	v_sub_f32_e32 v178, v226, v222
	v_sub_f32_e32 v179, v227, v223
	v_exp_f32_e64 v220, -|v68|
	v_exp_f32_e64 v221, -|v69|
	v_exp_f32_e64 v222, -|v70|
	v_exp_f32_e64 v223, -|v71|
	v_min_f32_e64 v224, 0, -v68
	v_min_f32_e64 v225, 0, -v69
	v_min_f32_e64 v226, 0, -v70
	v_min_f32_e64 v227, 0, -v71
	v_add_f32_e32 v220, 1.0, v220
	v_add_f32_e32 v221, 1.0, v221
	v_add_f32_e32 v222, 1.0, v222
	v_add_f32_e32 v223, 1.0, v223
	v_log_f32_e32 v220, v220
	v_log_f32_e32 v221, v221
	v_log_f32_e32 v222, v222
	v_log_f32_e32 v223, v223
	v_sub_f32_e32 v182, v224, v220
	v_sub_f32_e32 v184, v225, v221
	v_sub_f32_e32 v185, v226, v222
	v_sub_f32_e32 v198, v227, v223
	v_exp_f32_e64 v220, -|v72|
	v_exp_f32_e64 v221, -|v73|
	v_exp_f32_e64 v222, -|v74|
	v_exp_f32_e64 v223, -|v75|
	v_min_f32_e64 v224, 0, -v72
	v_min_f32_e64 v225, 0, -v73
	v_min_f32_e64 v226, 0, -v74
	v_min_f32_e64 v227, 0, -v75
	v_add_f32_e32 v220, 1.0, v220
	v_add_f32_e32 v221, 1.0, v221
	v_add_f32_e32 v222, 1.0, v222
	v_add_f32_e32 v223, 1.0, v223
	v_log_f32_e32 v220, v220
	v_log_f32_e32 v221, v221
	v_log_f32_e32 v222, v222
	v_log_f32_e32 v223, v223
	v_sub_f32_e32 v200, v224, v220
	v_sub_f32_e32 v201, v225, v221
	v_sub_f32_e32 v202, v226, v222
	v_sub_f32_e32 v203, v227, v223
	v_exp_f32_e64 v220, -|v76|
	v_exp_f32_e64 v221, -|v77|
	v_exp_f32_e64 v222, -|v78|
	v_exp_f32_e64 v223, -|v79|
	v_min_f32_e64 v224, 0, -v76
	v_min_f32_e64 v225, 0, -v77
	v_min_f32_e64 v226, 0, -v78
	v_min_f32_e64 v227, 0, -v79
	v_add_f32_e32 v220, 1.0, v220
	v_add_f32_e32 v221, 1.0, v221
	v_add_f32_e32 v222, 1.0, v222
	v_add_f32_e32 v223, 1.0, v223
	v_log_f32_e32 v220, v220
	v_log_f32_e32 v221, v221
	v_log_f32_e32 v222, v222
	v_log_f32_e32 v223, v223
	v_sub_f32_e32 v204, v224, v220
	v_sub_f32_e32 v205, v225, v221
	v_sub_f32_e32 v206, v226, v222
	v_sub_f32_e32 v207, v227, v223
	v_add_f32_e32 v220, v176, v177
	v_add_f32_e32 v221, v182, v184
	v_add_f32_e32 v222, v200, v201
	v_add_f32_e32 v223, v204, v205
	v_add_f32_e32 v224, v178, v179
	v_add_f32_e32 v225, v185, v198
	v_add_f32_e32 v226, v202, v203
	v_add_f32_e32 v227, v206, v207
	v_add_f32_e32 v220, v220, v224
	v_add_f32_e32 v221, v221, v225
	v_add_f32_e32 v222, v222, v226
	v_add_f32_e32 v223, v223, v227
	ds_bpermute_b32 v224, v191, v220
	ds_bpermute_b32 v225, v191, v221
	ds_bpermute_b32 v226, v191, v222
	ds_bpermute_b32 v227, v191, v223
	v_add_f32_e32 v64, v64, v176
	v_add_f32_e32 v65, v65, v177
	v_add_f32_e32 v66, v66, v178
	v_add_f32_e32 v67, v67, v179
	v_add_f32_e32 v68, v68, v182
	v_add_f32_e32 v69, v69, v184
	v_add_f32_e32 v70, v70, v185
	v_add_f32_e32 v71, v71, v198
	v_add_f32_e32 v72, v72, v200
	v_add_f32_e32 v73, v73, v201
	v_add_f32_e32 v74, v74, v202
	v_add_f32_e32 v75, v75, v203
	v_add_f32_e32 v76, v76, v204
	v_add_f32_e32 v77, v77, v205
	v_add_f32_e32 v78, v78, v206
	v_add_f32_e32 v79, v79, v207
	s_waitcnt lgkmcnt(0)
; #define LAS __attribute__((address_space(3)))
; __device__ __forceinline__ unsigned pk2(float lo, float hi) { unsigned r; asm("v_cvt_pk_bf16_f32 %0, %1, %2" : "=v"(r) : "v"(lo), "v"(hi)); return r; }
; template <bool sample> __device__ __forceinline__ void attn_task(const Args& a, LAS unsigned char* vl, int lane, int task) {
;     ...
;         for (int j = 0; j < 4; ++j) { gs[j] = (l1[4 * j] + l1[4 * j + 1]) + (l1[4 * j + 2] + l1[4 * j + 3]); og[j] = __shfl_xor(gs[j], 32); }
; #pragma unroll
;         for (int j = 3; j >= 0; --j) { A[j] = tot + (h == 0 ? og[j] : 0.f); tot += gs[j] + og[j]; }
;         float p[16];
; #pragma unroll
;         for (int j = 0; j < 4; ++j) {
;             float sfx = run + A[j];
; #pragma unroll
;             for (int i = 3; i >= 0; --i) {
;                 const int key = kp0 + 8 * j + 4 * h + i;
;                 const float w = __builtin_amdgcn_exp2f((x[4 * j + i] + l1[4 * j + i]) + sfx);
;                 p[4 * j + i] = key < qpos ? w : 0.f;
;                 sfx += l1[4 * j + i];
;             }
;         }
;         run += tot;
;         bf16x8 pf[2];
; #pragma unroll
;         for (int s = 0; s < 2; ++s) { u32x4 w; w.x = pk2(p[8 * s], p[8 * s + 1]); w.y = pk2(p[8 * s + 2], p[8 * s + 3]); w.z = pk2(p[8 * s + 4], p[8 * s + 5]); w.w = pk2(p[8 * s + 6], p[8 * s + 7]);
;             pf[s] = __builtin_bit_cast(bf16x8, w); }
;         __builtin_amdgcn_sched_barrier(0);
; #pragma unroll
;         for (int i = 0; i < 8; ++i) *(LAS u32x4*)(vl + (2 * (lane >> 2) + (i >> 2)) * VROW + ((i & 3) * 4 + (lane & 3)) * 16) = vr[i];
;         asm volatile("" ::: "memory");
; #pragma unroll
;         for (int db = 0; db < 4; ++db)
; #pragma unroll
;             for (int s = 0; s < 2; ++s) {
;                 const s16x4 lo = __builtin_amdgcn_ds_read_tr16_b64_v4i16((LAS s16x4*)(vl + troff + (16 * s) * VROW + db * 64));
;                 const s16x4 hi = __builtin_amdgcn_ds_read_tr16_b64_v4i16((LAS s16x4*)(vl + troff + (16 * s + 8) * VROW + db * 64));
;                 const bf16x8 vb = __builtin_shufflevector(lo, hi, 0, 1, 2, 3, 4, 5, 6, 7);
;                 O[db] = __builtin_amdgcn_mfma_f32_32x32x16_bf16(pf[s], vb, O[db], 0, 0, 0);
;             }
;         asm volatile("" ::: "memory");
;         if (__all((!valid) || (run < -127.f))) break;
	v_add_f32_e32 v220, v220, v224
	v_add_f32_e32 v221, v221, v225
	v_add_f32_e32 v222, v222, v226
	v_add_f32_e32 v223, v223, v227
	v_cndmask_b32_e64 v224, 0, v224, s[36:37]
	v_cndmask_b32_e64 v225, 0, v225, s[36:37]
	v_cndmask_b32_e64 v226, 0, v226, s[36:37]
	v_cndmask_b32_e64 v227, 0, v227, s[36:37]
	v_add_f32_e32 v226, v223, v226
	v_add_f32_e32 v222, v223, v222
	v_add_f32_e32 v225, v222, v225
	v_add_f32_e32 v221, v222, v221
	v_add_f32_e32 v224, v221, v224
	v_add_f32_e32 v183, v221, v220
	v_add_f32_e32 v228, v199, v224
	v_add_f32_e32 v221, v199, v225
	v_add_f32_e32 v222, v199, v226
	v_add_f32_e32 v223, v199, v227
	v_add_f32_e32 v67, v67, v228
	v_add_f32_e32 v71, v71, v221
	v_add_f32_e32 v75, v75, v222
	v_add_f32_e32 v79, v79, v223
	v_add_f32_e32 v228, v228, v179
	v_add_f32_e32 v221, v221, v198
	v_add_f32_e32 v222, v222, v203
	v_add_f32_e32 v223, v223, v207
	v_add_f32_e32 v66, v66, v228
	v_add_f32_e32 v70, v70, v221
	v_add_f32_e32 v74, v74, v222
	v_add_f32_e32 v78, v78, v223
	v_add_f32_e32 v228, v228, v178
	v_add_f32_e32 v221, v221, v185
	v_add_f32_e32 v222, v222, v202
	v_add_f32_e32 v223, v223, v206
	v_add_f32_e32 v65, v65, v228
	v_add_f32_e32 v69, v69, v221
	v_add_f32_e32 v73, v73, v222
	v_add_f32_e32 v77, v77, v223
	v_add_f32_e32 v228, v228, v177
	v_add_f32_e32 v221, v221, v184
	v_add_f32_e32 v222, v222, v201
	v_add_f32_e32 v223, v223, v205
	v_add_f32_e32 v64, v64, v228
	v_add_f32_e32 v68, v68, v221
	v_add_f32_e32 v72, v72, v222
	v_add_f32_e32 v76, v76, v223
	v_exp_f32_e32 v64, v64
	v_exp_f32_e32 v65, v65
	v_exp_f32_e32 v66, v66
	v_exp_f32_e32 v67, v67
	v_exp_f32_e32 v68, v68
	v_exp_f32_e32 v69, v69
	v_exp_f32_e32 v70, v70
	v_exp_f32_e32 v71, v71
	v_exp_f32_e32 v72, v72
	v_exp_f32_e32 v73, v73
	v_exp_f32_e32 v74, v74
	v_exp_f32_e32 v75, v75
	v_exp_f32_e32 v76, v76
	v_exp_f32_e32 v77, v77
	v_exp_f32_e32 v78, v78
	v_exp_f32_e32 v79, v79
	v_cvt_pk_bf16_f32 v64, v64, v65
	v_cvt_pk_bf16_f32 v65, v66, v67
	v_cvt_pk_bf16_f32 v66, v68, v69
	v_cvt_pk_bf16_f32 v67, v70, v71
	v_cvt_pk_bf16_f32 v68, v72, v73
	v_cvt_pk_bf16_f32 v69, v74, v75
	v_cvt_pk_bf16_f32 v70, v76, v77
	v_cvt_pk_bf16_f32 v71, v78, v79
	s_waitcnt vmcnt(15)
	ds_write_b128 v211, v[144:147]
	s_waitcnt vmcnt(14)
	ds_write_b128 v211, v[148:151] offset:64
	s_waitcnt vmcnt(13)
	ds_write_b128 v211, v[152:155] offset:128
	s_waitcnt vmcnt(12)
	ds_write_b128 v211, v[156:159] offset:192
	s_waitcnt vmcnt(11)
	ds_write_b128 v217, v[160:163]
	s_waitcnt vmcnt(10)
	ds_write_b128 v217, v[164:167] offset:64
	s_waitcnt vmcnt(9)
	ds_write_b128 v217, v[168:171] offset:128
	s_waitcnt vmcnt(8)
	ds_write_b128 v217, v[172:175] offset:192
	ds_read_b64_tr_b16 v[74:75], v218 offset:2560
	ds_read_b64_tr_b16 v[72:73], v218
	ds_read_b64_tr_b16 v[76:77], v218 offset:64
	ds_read_b64_tr_b16 v[144:145], v218 offset:128
	ds_read_b64_tr_b16 v[148:149], v218 offset:192
	ds_read_b64_tr_b16 v[78:79], v218 offset:2624
	ds_read_b64_tr_b16 v[146:147], v218 offset:2688
	ds_read_b64_tr_b16 v[150:151], v218 offset:2752
	s_waitcnt lgkmcnt(6)
	v_mfma_f32_32x32x16_bf16 v[48:63], v[64:67], v[72:75], v[48:63]
	ds_read_b64_tr_b16 v[74:75], v218 offset:7680
	v_add_f32_e32 v199, v199, v183
	v_cmp_gt_f32_e32 vcc, s80, v199
	s_or_b64 s[28:29], s[38:39], vcc
	s_waitcnt vmcnt(0)
	v_mov_b64_e32 v[178:179], v[142:143]
	v_mov_b64_e32 v[176:177], v[140:141]
	s_waitcnt lgkmcnt(3)
	v_mfma_f32_32x32x16_bf16 v[32:47], v[64:67], v[76:79], v[32:47]
	s_waitcnt lgkmcnt(2)
	v_mfma_f32_32x32x16_bf16 v[16:31], v[64:67], v[144:147], v[16:31]
	s_waitcnt lgkmcnt(1)
	v_mfma_f32_32x32x16_bf16 v[0:15], v[64:67], v[148:151], v[0:15]
	ds_read_b64_tr_b16 v[72:73], v218 offset:5120
	ds_read_b64_tr_b16 v[64:65], v218 offset:5184
	ds_read_b64_tr_b16 v[76:77], v218 offset:5248
	ds_read_b64_tr_b16 v[144:145], v218 offset:5312
	ds_read_b64_tr_b16 v[66:67], v218 offset:7744
	ds_read_b64_tr_b16 v[78:79], v218 offset:7808
	ds_read_b64_tr_b16 v[146:147], v218 offset:7872
	s_waitcnt lgkmcnt(6)
	v_mfma_f32_32x32x16_bf16 v[48:63], v[68:71], v[72:75], v[48:63]
	s_waitcnt lgkmcnt(2)
	v_mfma_f32_32x32x16_bf16 v[32:47], v[68:71], v[64:67], v[32:47]
	v_add_co_u32_e64 v64, s[0:1], s26, -1
	s_nop 0
	v_readfirstlane_b32 s26, v64
	v_cndmask_b32_e64 v64, 0, 1, s[28:29]
	v_cmp_ne_u32_e32 vcc, 0, v64
	s_cmp_lg_u64 vcc, exec
	s_cselect_b64 s[28:29], -1, 0
	s_waitcnt lgkmcnt(1)
	v_mfma_f32_32x32x16_bf16 v[16:31], v[68:71], v[76:79], v[16:31]
	s_and_b64 s[0:1], s[0:1], s[28:29]
	s_add_i32 s25, s25, -1
	s_sub_i32 s24, s24, 32
	s_and_b64 vcc, exec, s[0:1]
	s_waitcnt lgkmcnt(0)
	v_mfma_f32_32x32x16_bf16 v[0:15], v[68:71], v[144:147], v[0:15]
	s_cbranch_vccnz .Lsb_nm
	v_readlane_b32 s24, v255, 18
	v_readlane_b32 s25, v255, 19
	s_branch .LBB0_61
